# window for L0 FFN2 gate/up takes 9 items per WG, others 7
# baseline (speedup 1.0000x reference)
; __device__ __forceinline__ unsigned cvt_pk_bf16(float lo, float hi) { unsigned r; asm volatile("v_cvt_pk_bf16_f32 %0, %1, %2" : "=v"(r) : "v"(lo), "v"(hi)); return r; }
; #define LAS __attribute__((address_space(3)))
; __device__ __forceinline__ void tr_item_cu(const float* __restrict__ W, int K, int N, bf16* __restrict__ WT, const float* rowgain, int mode, LAS unsigned char* buf, int item, int wave, int lane) {
;     const int nblk = N >> 7, kb = item / nblk, nb = item - kb * nblk, k0 = 256 * kb, n0 = 128 * nb;
;     const int hr = lane >> 5, c = lane & 31, kw = 32 * wave + 16 * hr;
;     f32x4 v[16];
;     const float* src = W + (size_t)(k0 + kw) * N + n0 + 4 * c;
; #pragma unroll
;     for (int j = 0; j < 16; ++j) v[j] = __builtin_nontemporal_load((const f32x4*)(src + (size_t)j * N));
;     if (rowgain) {
; #pragma unroll
;         for (int q = 0; q < 4; ++q) { const f32x4 r4 = *(const f32x4*)(rowgain + k0 + kw + 4 * q);
; #pragma unroll
;             for (int e = 0; e < 4; ++e) v[4 * q + e] = v[4 * q + e] * r4[e]; }
;     }
; #pragma unroll
;     for (int i = 0; i < 4; ++i) {
;         u32x4 lo, hi;
;         lo.x = pg8::cvt_pk_bf16(v[0][i], v[1][i]);   lo.y = pg8::cvt_pk_bf16(v[2][i], v[3][i]);   lo.z = pg8::cvt_pk_bf16(v[4][i], v[5][i]);   lo.w = pg8::cvt_pk_bf16(v[6][i], v[7][i]);
;         hi.x = pg8::cvt_pk_bf16(v[8][i], v[9][i]);   hi.y = pg8::cvt_pk_bf16(v[10][i], v[11][i]); hi.z = pg8::cvt_pk_bf16(v[12][i], v[13][i]); hi.w = pg8::cvt_pk_bf16(v[14][i], v[15][i]);
;         LAS unsigned char* p = buf + (4 * c + i) * TCP + kw * 2;
;         *(LAS u32x4*)p = lo; *(LAS u32x4*)(p + 16) = hi;
;     }
;     __syncthreads();
; #pragma unroll
;     for (int m = 0; m < 8; ++m) { const int row = 16 * wave + 2 * m + hr;
;         const u32x4 o = *(const LAS u32x4*)(buf + row * TCP + c * 16);
;         asm volatile("global_store_dwordx4 %0, %1, off sc1\n\ts_nop 1" :: "v"(WT + (size_t)row_map(mode, n0 + row) * K + k0 + 8 * c), "v"(o) : "memory"); }
.Ldc_pre:
	v_ashrrev_i32_e32 v3, 5, v2
	v_lshl_add_u32 v77, s73, 4, v3
	v_add_u32_e32 v82, 2, v77
	v_lshrrev_b32_e32 v6, 2, v82
	v_and_b32_e32 v84, 16, v6
	v_lshlrev_b32_e32 v6, 2, v82
	v_and_b32_e32 v6, 16, v6
	v_lshrrev_b32_e32 v7, 1, v82
	v_add_u32_e32 v86, 4, v77
	v_and_or_b32 v85, v7, 12, v6
	v_lshrrev_b32_e32 v6, 2, v86
	v_and_b32_e32 v88, 16, v6
	v_lshlrev_b32_e32 v6, 2, v86
	v_and_b32_e32 v6, 16, v6
	v_lshrrev_b32_e32 v7, 1, v86
	v_add_u32_e32 v90, 6, v77
	v_and_or_b32 v89, v7, 12, v6
	v_lshrrev_b32_e32 v6, 2, v90
	v_and_b32_e32 v92, 16, v6
	v_lshlrev_b32_e32 v6, 2, v90
	v_and_b32_e32 v6, 16, v6
	v_lshrrev_b32_e32 v7, 1, v90
	v_add_u32_e32 v97, 10, v77
	v_and_or_b32 v93, v7, 12, v6
	v_lshrrev_b32_e32 v7, 2, v97
	s_add_u32 s36, s12, 0x900000
	v_and_b32_e32 v99, 16, v7
	v_lshlrev_b32_e32 v7, 2, v97
	s_addc_u32 s37, s13, 0
	s_load_dwordx2 s[12:13], s[0:1], 0x8
	s_load_dwordx4 s[4:7], s[0:1], 0x20
	s_load_dwordx4 s[8:11], s[0:1], 0x58
	s_load_dwordx2 s[14:15], s[0:1], 0x30
	s_load_dwordx2 s[16:17], s[0:1], 0x78
	v_and_b32_e32 v7, 16, v7
	v_lshrrev_b32_e32 v8, 1, v97
	v_add_u32_e32 v101, 12, v77
	v_and_or_b32 v100, v8, 12, v7
	v_lshrrev_b32_e32 v7, 2, v101
	v_and_b32_e32 v103, 16, v7
	v_lshlrev_b32_e32 v7, 2, v101
	v_and_b32_e32 v7, 16, v7
	v_lshrrev_b32_e32 v8, 1, v101
	v_add_u32_e32 v105, 14, v77
	s_lshl_b32 s18, s73, 5
	v_add_u32_e32 v94, 8, v77
	v_and_or_b32 v104, v8, 12, v7
	v_lshrrev_b32_e32 v7, 2, v105
	v_and_b32_e32 v4, 31, v2
	v_lshl_add_u32 v66, v3, 4, s18
	v_lshrrev_b32_e32 v5, 2, v77
	v_lshlrev_b32_e32 v3, 2, v3
	v_lshrrev_b32_e32 v6, 2, v94
	v_and_b32_e32 v107, 16, v7
	v_lshlrev_b32_e32 v7, 2, v105
	v_lshlrev_b32_e32 v2, 2, v4
	v_mov_b32_e32 v69, 0
	v_mul_u32_u24_e32 v76, 0x840, v4
	v_lshlrev_b32_e32 v78, 4, v4
	v_lshlrev_b32_e32 v4, 3, v4
	s_movk_i32 s18, 0x210
	v_and_b32_e32 v80, 0x7f, v77
	v_and_b32_e32 v81, 16, v5
	v_and_b32_e32 v3, 16, v3
	v_lshrrev_b32_e32 v5, 1, v77
	v_and_b32_e32 v83, 0x7f, v82
	v_and_b32_e32 v87, 0x7f, v86
	v_and_b32_e32 v91, 0x7f, v90
	v_and_b32_e32 v95, 0x7f, v94
	v_and_b32_e32 v96, 16, v6
	v_lshrrev_b32_e32 v6, 1, v94
	v_and_b32_e32 v98, 0x7f, v97
	v_and_b32_e32 v102, 0x7f, v101
	v_and_b32_e32 v106, 0x7f, v105
	v_and_b32_e32 v7, 16, v7
	v_lshrrev_b32_e32 v8, 1, v105
	v_ashrrev_i32_e32 v67, 31, v66
	v_lshlrev_b32_e32 v75, 1, v66
	v_mul_lo_u32 v79, v77, s18
	v_and_or_b32 v108, v8, 12, v7
	v_or_b32_e32 v109, 0x80, v80
	v_or_b32_e32 v110, 0x80, v83
	v_or_b32_e32 v111, 0x80, v87
	v_or_b32_e32 v112, 0x80, v91
	v_or_b32_e32 v113, 0x80, v95
	v_or_b32_e32 v114, 0x80, v98
	v_or_b32_e32 v115, 0x80, v102
	v_or_b32_e32 v116, 0x80, v106
	v_and_or_b32 v117, v5, 12, v3
	v_and_or_b32 v118, v6, 12, v3
	s_mov_b32 s19, 0
	s_sub_i32 s38, 0, s72
	s_sub_i32 s39, 0x137f, s72
	v_lshlrev_b32_e32 v70, 2, v2
	v_mov_b32_e32 v71, v69
	s_movk_i32 s40, 0xff00
	s_movk_i32 s41, 0xf7ff
	s_movk_i32 s42, 0xffe3
	v_lshlrev_b32_e32 v68, 1, v4
	s_mov_b32 s43, 0
	s_mov_b32 s44, s72
	s_cmp_lg_u32 s98, 0
	s_cbranch_scc1 .Ldc_ovr
	v_readlane_b32 s100, v254, 2
	s_movk_i32 s101, 0x137f
	s_nop 1
	s_mov_b32 s99, s100
	s_cmpk_lg_i32 s100, 0x100
	s_cbranch_scc1 .LBB0_33
	s_cmpk_lt_i32 s72, 0x80
	s_cbranch_scc1 .Ldc_lowhalf
	s_addk_i32 s44, 3296
	s_sub_i32 s38, 0, s44
	s_sub_i32 s39, 0x137f, s44
	s_branch .LBB0_33
.Ldc_lowhalf:
	s_addk_i32 s44, 2496
	s_sub_i32 s38, 0, s44
	s_sub_i32 s39, 0x137f, s44
	s_movk_i32 s100, 1056
	s_branch .LBB0_33

; __global__ void __launch_bounds__(NTHREADS, 2) mega_fwd(Args args) {
;     ...
;         for (int it = bid; it < DEPTH * I_LAYER; it += G, nbuf ^= 1) {
;             const int itr = DEPTH * I_LAYER - 1 - it;
;             const int l = itr / I_LAYER; int r = itr - l * I_LAYER;
;             unsigned char* WL = P_WL(l);
;             const float* W; int K, N, mode = 0; bf16* WT; const float* rg = nullptr;
;             if (r < 3 * I_GU) { const int w = r / I_GU; r -= w * I_GU;
;                 if (w < 2) { W = args.in[2 + w] + (size_t)l * D * FF; K = D; N = FF; WT = (bf16*)(WL + OFF_WGU1); rg = args.in[1] + (size_t)l * D; mode = 1 + w; }
;                 else { W = args.in[4] + (size_t)l * FF * D; K = FF; N = D; WT = (bf16*)(WL + OFF_WD1); } }
;             else if ((r -= 3 * I_GU) < 3 * I_GU) { const int w = r / I_GU; r -= w * I_GU;
;                 if (w < 2) { W = args.in[13 + w] + (size_t)l * D * FF; K = D; N = FF; WT = (bf16*)(WL + OFF_WGU2); rg = args.in[12] + (size_t)l * D; mode = 1 + w; }
;                 else { W = args.in[15] + (size_t)l * FF * D; K = FF; N = D; WT = (bf16*)(WL + OFF_WD2); } }
;             else if ((r -= 3 * I_GU) < I_IN) { W = args.in[6] + (size_t)l * D * INW; K = D; N = INW; WT = (bf16*)(WL + OFF_WIN); rg = args.in[5] + (size_t)l * D; mode = 3; }
;             else { r -= I_IN; W = args.in[11] + (size_t)l * D * D; K = D; N = D; WT = (bf16*)(WL + OFF_WOUT); }
;             tr_item_cu(W, K, N, WT, rg, mode, lds + nbuf * TC_BUF, r, wave, lane);
;         }
.Ldc_setup:
	v_readlane_b32 s4, v255, 28
	v_readlane_b32 s0, v255, 62
	v_readlane_b32 s1, v255, 63
	v_readlane_b32 s12, v254, 0
	v_readlane_b32 s13, v254, 1
	v_mov_b32_e32 v2, v211
	s_cmp_lg_u32 s4, 0
	s_cselect_b32 s4, 2, 0
	s_and_b32 s5, s98, 3
	s_add_i32 s4, s4, s5
	s_lshr_b32 s5, s98, 2
	s_lshl_b32 s4, s4, 2
	s_or_b32 s4, s4, s5
	s_mov_b32 s99, 1
	s_mov_b32 s101, 0
	s_cmp_eq_u32 s4, 4
	s_cselect_b32 s99, 2400, s99
	s_cselect_b32 s101, 2495, s101
	s_cmp_eq_u32 s4, 5
	s_cselect_b32 s99, 2624, s99
	s_cselect_b32 s101, 3423, s101
	s_cmp_eq_u32 s4, 8
	s_cselect_b32 s99, 0, s99
	s_cselect_b32 s101, 127, s101
	s_cmp_eq_u32 s4, 9
	s_cselect_b32 s99, 1376, s99
	s_cselect_b32 s101, 2399, s101
	s_cmp_eq_u32 s4, 12
	s_cselect_b32 s99, 128, s99
	s_cselect_b32 s101, 383, s101
	s_cmp_eq_u32 s4, 13
	s_cselect_b32 s99, 736, s99
	s_cselect_b32 s101, 1375, s101
	s_cmp_eq_u32 s4, 16
	s_cselect_b32 s99, 384, s99
	s_cselect_b32 s101, 735, s101
	s_cmp_gt_i32 s99, s101
	s_cbranch_scc1 .Ldc_finish
	s_sub_i32 s5, s72, 0x80
	s_add_i32 s99, s99, s5
	s_cmp_gt_i32 s99, s101
	s_cbranch_scc1 .Ldc_nextpass
	s_movk_i32 s100, 0x80
	s_waitcnt lgkmcnt(0)
	s_nop 4
	s_branch .Ldc_pre
